# prompt attention loop: next-tile K/V global loads hoisted ahead of QK, LDS fragment ring in fresh VGPRs
# speedup vs baseline: 1.0003x; 1.0003x over previous
; #define MFMA(a, b, c) __builtin_amdgcn_mfma_f32_32x32x16_bf16((a), (b), (c), 0, 0, 0)
; #define ATT_SSTORE() do { \
;     *(uint4*)(ldsK) = rk0; *(uint4*)(ldsK + 16 * KLD) = rk1; *(uint4*)(ldsK + 32 * KLD) = rk2; *(uint4*)(ldsK + 48 * KLD) = rk3; \
;     if (DQK == 192) { *(uint4*)(ldsR) = rk4; *(uint4*)(ldsR + 32 * KLD) = rk5; } \
;     ATT_VST(0, rv0); ATT_VST(1, rv1); ATT_VST(2, rv2); ATT_VST(3, rv3); } while (0)
;     ...
;   ATT_GLOAD(rev ? nkt - 1 : 0);
;   for (int kt = 0; kt < nkt; kt++) {
;     __syncthreads();
;     ATT_SSTORE();
;     __syncthreads();
;     const int ktile = rev ? nkt - 1 - kt : kt;
;     const bool active = ktile < nkt_w;
;     f32x16 s[2];
;     if (active) {
;       const f32x16 zero16 = {0.f, 0.f, 0.f, 0.f, 0.f, 0.f, 0.f, 0.f, 0.f, 0.f, 0.f, 0.f, 0.f, 0.f, 0.f, 0.f};
;       bf16x8 qx[(NQF > NQR) ? (NQF - NQR) : 1];
;       if (NQF > NQR) {
; #pragma unroll
;         for (int ks = NQR; ks < NQF; ks++) qx[ks - NQR] = *(const bf16x8*)(Qs + (w * 32 + r) * 72 + (ks - NQR) * 16 + h * 8);
;       }
;       __builtin_amdgcn_s_setprio(1);
; #pragma unroll
;       for (int ks = 0; ks < NQF; ks++) {
; #pragma unroll
;         for (int mt = 0; mt < 2; mt++) {
;           const bf16x8 kf = *(const bf16x8*)(Ks + (mt * 32 + r) * KLD + ks * 16 + h * 8);
;           s[mt] = MFMA(kf, (ks < NQR) ? qf[ks < NQR ? ks : 0] : qx[ks >= NQR ? ks - NQR : 0], (ks == 0) ? zero16 : s[mt]);
;         }
;       }
;       __builtin_amdgcn_s_setprio(0);
;     }
;     __builtin_amdgcn_sched_barrier(0);
;     if (kt + 1 < nkt) ATT_GLOAD(rev ? ktile - 1 : ktile + 1);
.LBB0_656:
	s_waitcnt lgkmcnt(0)
	s_barrier
	s_waitcnt vmcnt(9)
	ds_write_b128 v176, v[132:135]
	s_waitcnt vmcnt(8)
	ds_write_b128 v176, v[136:139] offset:6400
	s_waitcnt vmcnt(7)
	ds_write_b128 v176, v[140:143] offset:12800
	s_waitcnt vmcnt(6)
	ds_write_b128 v176, v[144:147] offset:19200
	s_waitcnt vmcnt(5)
	ds_write_b128 v174, v[152:155] offset:256
	s_waitcnt vmcnt(4)
	ds_write_b128 v174, v[148:151] offset:13056
	v_mov_b32_e32 v132, s2
	v_cndmask_b32_e64 v132, v132, v192, s[8:9]
	v_add_u32_e32 v193, 0x6400, v178
	v_add_u32_e32 v194, 0x7500, v178
	v_add_u32_e32 v195, 0x8600, v178
	v_add_u32_e32 v196, 0x9700, v178
	v_cmp_lt_i32_e64 s[10:11], v132, v188
	s_waitcnt vmcnt(1)
	ds_write2_b64 v193, v[168:169], v[170:171] offset1:1
	ds_write2_b64 v194, v[156:157], v[158:159] offset1:1
	ds_write2_b64 v195, v[160:161], v[162:163] offset1:1
	s_waitcnt vmcnt(0)
	ds_write2_b64 v196, v[164:165], v[166:167] offset1:1
	s_waitcnt lgkmcnt(0)
	s_barrier
	v_add_u32_e32 v156, v132, v191
	v_ashrrev_i32_e32 v157, 31, v156
	v_lshlrev_b32_e32 v148, 6, v156
	v_lshlrev_b64 v[156:157], 14, v[156:157]
	v_lshl_add_u64 v[156:157], v[172:173], 0, v[156:157]
	v_lshl_add_u64 v[160:161], v[156:157], 0, v[0:1]
	s_movk_i32 s3, 0x1000
	v_add_co_u32_e32 v156, vcc, s3, v160
	v_or_b32_e32 v134, 16, v148
	s_nop 0
	v_addc_co_u32_e32 v157, vcc, 0, v161, vcc
	v_or_b32_e32 v150, 32, v148
	v_or_b32_e32 v142, 48, v148
	v_add_co_u32_e32 v162, vcc, 0x2000, v160
	v_ashrrev_i32_e32 v149, 31, v148
	v_ashrrev_i32_e32 v135, 31, v134
	v_ashrrev_i32_e32 v151, 31, v150
	v_ashrrev_i32_e32 v143, 31, v142
	v_addc_co_u32_e32 v163, vcc, 0, v161, vcc
	v_lshlrev_b64 v[132:133], 8, v[148:149]
	v_lshlrev_b64 v[134:135], 8, v[134:135]
	v_lshlrev_b64 v[140:141], 8, v[150:151]
	v_lshlrev_b64 v[142:143], 8, v[142:143]
	v_lshlrev_b64 v[148:149], 7, v[148:149]
	v_lshlrev_b64 v[150:151], 7, v[150:151]
	v_add_co_u32_e32 v164, vcc, 0x3000, v160
	v_lshl_add_u64 v[132:133], v[180:181], 0, v[132:133]
	v_lshl_add_u64 v[136:137], v[180:181], 0, v[134:135]
	v_lshl_add_u64 v[140:141], v[180:181], 0, v[140:141]
	v_lshl_add_u64 v[144:145], v[180:181], 0, v[142:143]
	v_lshl_add_u64 v[148:149], v[182:183], 0, v[148:149]
	v_lshl_add_u64 v[150:151], v[182:183], 0, v[150:151]
	v_addc_co_u32_e32 v165, vcc, 0, v161, vcc
	global_load_dwordx4 v[132:135], v[132:133], off
	s_nop 0
	global_load_dwordx4 v[136:139], v[136:137], off
	s_nop 0
	global_load_dwordx4 v[140:143], v[140:141], off
	s_nop 0
	global_load_dwordx4 v[144:147], v[144:145], off
	s_nop 0
	global_load_dwordx4 v[152:155], v[148:149], off
	s_nop 0
	global_load_dwordx4 v[148:151], v[150:151], off
	s_nop 0
	global_load_dwordx4 v[168:171], v[160:161], off
	s_nop 0
	global_load_dwordx4 v[156:159], v[156:157], off
	s_nop 0
	global_load_dwordx4 v[160:163], v[162:163], off
	s_nop 0
	global_load_dwordx4 v[164:167], v[164:165], off
	s_and_saveexec_b64 s[26:27], s[10:11]
	s_cbranch_execz .LBB0_655
	v_add_u32_e32 v197, v14, v190
	ds_read_b128 v[214:217], v197 offset:43008
	ds_read_b128 v[218:221], v197 offset:43040
	ds_read_b128 v[222:225], v197 offset:43072
	ds_read_b128 v[198:201], v197 offset:43104
	v_add_u32_e32 v197, v14, v189
	ds_read_b128 v[228:231], v197
	ds_read_b128 v[232:235], v197 offset:12800
	ds_read_b128 v[236:239], v197 offset:32
	ds_read_b128 v[240:243], v197 offset:12832
	ds_read_b128 v[244:247], v197 offset:64
	ds_read_b128 v[248:251], v197 offset:12864
	ds_read_b128 v[252:255], v197 offset:96
	s_setprio 1
	s_waitcnt lgkmcnt(6)
	v_mfma_f32_32x32x16_bf16 v[96:111], v[228:231], v[128:131], 0
	ds_read_b128 v[228:231], v197 offset:12896
	s_waitcnt lgkmcnt(6)
	v_mfma_f32_32x32x16_bf16 v[80:95], v[232:235], v[128:131], 0
	ds_read_b128 v[232:235], v197 offset:128
	s_waitcnt lgkmcnt(6)
	v_mfma_f32_32x32x16_bf16 v[96:111], v[236:239], v[124:127], v[96:111]
	ds_read_b128 v[236:239], v197 offset:12928
	s_waitcnt lgkmcnt(6)
	v_mfma_f32_32x32x16_bf16 v[80:95], v[240:243], v[124:127], v[80:95]
	ds_read_b128 v[240:243], v197 offset:160
	s_waitcnt lgkmcnt(6)
	v_mfma_f32_32x32x16_bf16 v[96:111], v[244:247], v[120:123], v[96:111]
	ds_read_b128 v[244:247], v197 offset:12960
	s_waitcnt lgkmcnt(6)
	v_mfma_f32_32x32x16_bf16 v[80:95], v[248:251], v[120:123], v[80:95]
	ds_read_b128 v[248:251], v197 offset:192
	s_waitcnt lgkmcnt(6)
	v_mfma_f32_32x32x16_bf16 v[96:111], v[252:255], v[116:119], v[96:111]
	ds_read_b128 v[252:255], v197 offset:12992
	s_waitcnt lgkmcnt(6)
	v_mfma_f32_32x32x16_bf16 v[80:95], v[228:231], v[116:119], v[80:95]
	ds_read_b128 v[228:231], v197 offset:224
	s_waitcnt lgkmcnt(6)
	v_mfma_f32_32x32x16_bf16 v[96:111], v[232:235], v[112:115], v[96:111]
	ds_read_b128 v[232:235], v197 offset:13024
	s_waitcnt lgkmcnt(6)
	v_mfma_f32_32x32x16_bf16 v[80:95], v[236:239], v[112:115], v[80:95]
	ds_read_b128 v[236:239], v197 offset:256
	s_waitcnt lgkmcnt(6)
	v_mfma_f32_32x32x16_bf16 v[96:111], v[240:243], v[10:13], v[96:111]
	ds_read_b128 v[240:243], v197 offset:13056
	s_waitcnt lgkmcnt(6)
; #define MFMA(a, b, c) __builtin_amdgcn_mfma_f32_32x32x16_bf16((a), (b), (c), 0, 0, 0)
;     ...
;       for (int ks = 0; ks < NQF; ks++) {
; #pragma unroll
;         for (int mt = 0; mt < 2; mt++) {
;           const bf16x8 kf = *(const bf16x8*)(Ks + (mt * 32 + r) * KLD + ks * 16 + h * 8);
;           s[mt] = MFMA(kf, (ks < NQR) ? qf[ks < NQR ? ks : 0] : qx[ks >= NQR ? ks - NQR : 0], (ks == 0) ? zero16 : s[mt]);
;         }
;       }
;       __builtin_amdgcn_s_setprio(0);
;     }
;     __builtin_amdgcn_sched_barrier(0);
;     if (kt + 1 < nkt) ATT_GLOAD(rev ? ktile - 1 : ktile + 1);
;     __builtin_amdgcn_sched_barrier(0);
;     if (active) {
;       float mx = s[0][0];
; #pragma unroll
;       for (int mt = 0; mt < 2; mt++)
; #pragma unroll
;         for (int i = 0; i < 16; i++) mx = fmaxf(mx, s[mt][i]);
;       mx = fmaxf(mx, __shfl_xor(mx, 32));
;       if (__builtin_amdgcn_ballot_w64(mx > m_run + 8.f) != 0ull) {
;         const float m_new = fmaxf(m_run, mx);
;         const float alpha = __builtin_amdgcn_exp2f(m_run - m_new);
;         m_run = m_new;
;         l_run *= alpha;
; #pragma unroll
;         for (int mc = 0; mc < 4; mc++)
; #pragma unroll
;           for (int i = 0; i < 16; i++) o[mc][i] *= alpha;
;       }
	v_mfma_f32_32x32x16_bf16 v[80:95], v[244:247], v[10:13], v[80:95]
	ds_read_b128 v[244:247], v197 offset:288
	s_waitcnt lgkmcnt(6)
	v_mfma_f32_32x32x16_bf16 v[96:111], v[248:251], v[6:9], v[96:111]
	ds_read_b128 v[248:251], v197 offset:13088
	s_waitcnt lgkmcnt(6)
	v_mfma_f32_32x32x16_bf16 v[80:95], v[252:255], v[6:9], v[80:95]
	ds_read_b128 v[252:255], v197 offset:320
	s_waitcnt lgkmcnt(6)
	v_mfma_f32_32x32x16_bf16 v[96:111], v[228:231], v[2:5], v[96:111]
	ds_read_b128 v[228:231], v197 offset:13120
	s_waitcnt lgkmcnt(6)
	v_mfma_f32_32x32x16_bf16 v[80:95], v[232:235], v[2:5], v[80:95]
	ds_read_b128 v[232:235], v197 offset:352
	s_waitcnt lgkmcnt(6)
	v_mfma_f32_32x32x16_bf16 v[96:111], v[236:239], v[214:217], v[96:111]
	ds_read_b128 v[236:239], v197 offset:13152
	s_waitcnt lgkmcnt(6)
	v_mfma_f32_32x32x16_bf16 v[80:95], v[240:243], v[214:217], v[80:95]
	s_waitcnt lgkmcnt(5)
	v_mfma_f32_32x32x16_bf16 v[96:111], v[244:247], v[218:221], v[96:111]
	s_waitcnt lgkmcnt(4)
	v_mfma_f32_32x32x16_bf16 v[80:95], v[248:251], v[218:221], v[80:95]
	s_waitcnt lgkmcnt(3)
	v_mfma_f32_32x32x16_bf16 v[96:111], v[252:255], v[222:225], v[96:111]
	s_waitcnt lgkmcnt(2)
	v_mfma_f32_32x32x16_bf16 v[80:95], v[228:231], v[222:225], v[80:95]
	s_waitcnt lgkmcnt(1)
	v_mfma_f32_32x32x16_bf16 v[96:111], v[232:235], v[198:201], v[96:111]
	s_waitcnt lgkmcnt(0)
	v_mfma_f32_32x32x16_bf16 v[80:95], v[236:239], v[198:201], v[80:95]
	s_setprio 0
	v_add_u32_e32 v222, v175, v177
	ds_read_b64 v[214:215], v222 offset:25600
	ds_read_b64 v[216:217], v222 offset:25616
	ds_read_b64 v[218:219], v222 offset:29952
	ds_read_b64 v[220:221], v222 offset:29968
	ds_read_b64 v[228:229], v222 offset:34304
	ds_read_b64 v[230:231], v222 offset:34320
	ds_read_b64 v[232:233], v222 offset:38656
	ds_read_b64 v[234:235], v222 offset:38672
	ds_read_b64 v[236:237], v222 offset:25632
	ds_read_b64 v[238:239], v222 offset:25648
	ds_read_b64 v[240:241], v222 offset:29984
	ds_read_b64 v[242:243], v222 offset:30000
	ds_read_b64 v[244:245], v222 offset:34336
	ds_read_b64 v[246:247], v222 offset:34352
	v_max_f32_e32 v197, v97, v97
	v_max_f32_e32 v198, v96, v96
	v_max_f32_e32 v197, v198, v197
	v_max3_f32 v197, v197, v98, v99
	v_max3_f32 v197, v197, v100, v101
	v_max3_f32 v197, v197, v102, v103
	v_max3_f32 v197, v197, v104, v105
	v_max3_f32 v197, v197, v106, v107
	v_max3_f32 v197, v197, v108, v109
	v_max3_f32 v197, v197, v110, v111
	v_max3_f32 v197, v197, v80, v81
	v_max3_f32 v197, v197, v82, v83
	v_max3_f32 v197, v197, v84, v85
	v_max3_f32 v197, v197, v86, v87
	v_max3_f32 v197, v197, v88, v89
	v_max3_f32 v197, v197, v90, v91
	v_max3_f32 v197, v197, v92, v93
	v_max3_f32 v197, v197, v94, v95
	v_mov_b32_e32 v198, v197
	s_nop 1
	v_permlane32_swap_b32_e32 v197, v198
	v_max_f32_e32 v197, v197, v198
	v_add_f32_e32 v198, 0x41000000, v179
	v_cmp_gt_f32_e32 vcc, v197, v198
	s_cbranch_vccz .LBB0_654
	v_max_f32_e32 v197, v197, v197
	v_max_f32_e32 v198, v179, v179
	v_max_f32_e32 v197, v198, v197
	v_sub_f32_e32 v179, v179, v197
	v_exp_f32_e32 v198, v179
	v_mov_b32_e32 v179, v197
	v_pk_mul_f32 v[78:79], v[78:79], v[198:199] op_sel_hi:[1,0]
	v_pk_mul_f32 v[76:77], v[76:77], v[198:199] op_sel_hi:[1,0]
	v_pk_mul_f32 v[74:75], v[74:75], v[198:199] op_sel_hi:[1,0]
	v_pk_mul_f32 v[72:73], v[72:73], v[198:199] op_sel_hi:[1,0]
	v_pk_mul_f32 v[70:71], v[70:71], v[198:199] op_sel_hi:[1,0]
	v_pk_mul_f32 v[68:69], v[68:69], v[198:199] op_sel_hi:[1,0]
	v_pk_mul_f32 v[66:67], v[66:67], v[198:199] op_sel_hi:[1,0]
	v_pk_mul_f32 v[64:65], v[64:65], v[198:199] op_sel_hi:[1,0]
	v_pk_mul_f32 v[62:63], v[62:63], v[198:199] op_sel_hi:[1,0]
	v_pk_mul_f32 v[60:61], v[60:61], v[198:199] op_sel_hi:[1,0]
	v_pk_mul_f32 v[58:59], v[58:59], v[198:199] op_sel_hi:[1,0]
	v_pk_mul_f32 v[56:57], v[56:57], v[198:199] op_sel_hi:[1,0]
	v_pk_mul_f32 v[54:55], v[54:55], v[198:199] op_sel_hi:[1,0]
	v_pk_mul_f32 v[52:53], v[52:53], v[198:199] op_sel_hi:[1,0]
	v_pk_mul_f32 v[50:51], v[50:51], v[198:199] op_sel_hi:[1,0]
	v_pk_mul_f32 v[48:49], v[48:49], v[198:199] op_sel_hi:[1,0]
	v_pk_mul_f32 v[46:47], v[46:47], v[198:199] op_sel_hi:[1,0]
	v_pk_mul_f32 v[44:45], v[44:45], v[198:199] op_sel_hi:[1,0]
	v_pk_mul_f32 v[42:43], v[42:43], v[198:199] op_sel_hi:[1,0]
	v_pk_mul_f32 v[40:41], v[40:41], v[198:199] op_sel_hi:[1,0]
	v_pk_mul_f32 v[38:39], v[38:39], v[198:199] op_sel_hi:[1,0]
	v_pk_mul_f32 v[36:37], v[36:37], v[198:199] op_sel_hi:[1,0]
	v_pk_mul_f32 v[34:35], v[34:35], v[198:199] op_sel_hi:[1,0]
	v_pk_mul_f32 v[32:33], v[32:33], v[198:199] op_sel_hi:[1,0]
	v_pk_mul_f32 v[30:31], v[30:31], v[198:199] op_sel_hi:[1,0]
	v_pk_mul_f32 v[28:29], v[28:29], v[198:199] op_sel_hi:[1,0]
	v_pk_mul_f32 v[26:27], v[26:27], v[198:199] op_sel_hi:[1,0]
	v_pk_mul_f32 v[24:25], v[24:25], v[198:199] op_sel_hi:[1,0]
	v_pk_mul_f32 v[22:23], v[22:23], v[198:199] op_sel_hi:[1,0]
	v_pk_mul_f32 v[20:21], v[20:21], v[198:199] op_sel_hi:[1,0]
	v_pk_mul_f32 v[18:19], v[18:19], v[198:199] op_sel_hi:[1,0]
	v_pk_mul_f32 v[16:17], v[16:17], v[198:199] op_sel_hi:[1,0]
	v_mul_f32_e32 v15, v15, v198
	s_branch .LBB0_654
